# static s_setprio 1 for waves 4-7 during the MLA attention units
# baseline (speedup 1.0000x reference)
; __global__ void __launch_bounds__(512, 2) mk_fwd(Args a_) {
;     ...
;             for (int ui = bid; ui < 1024 && !(MK_DUPS == 3 && rep == 1); ui += G) {
;                 const int rnd = ui >> 8, c0 = ui & 255, xcd = c0 & 7, w = c0 >> 3;
;                 const int bh = 8 * xcd + 2 * rnd + (w >> 4), b = bh >> 4, h = bh & 15, qb = (rnd & 1) ? 15 - (w & 15) : (w & 15);
;                 const size_t row0 = (size_t)b * SEQL + qb * 256, kr0 = (size_t)b * SEQL;
;                 attn_unit<12>(lds, tid, qn + row0 * 2048 + h * 128, 2048, qpe + row0 * 1024 + h * 64, 1024, kn + kr0 * 2048 + h * 128, 2048, kpe + kr0 * 64, 64,
;                               vb + kr0 * 2048 + h * 128, 2048, ya + row0 * 2048 + h * 128, 2048, 4 * qb + 4, 4 * qb + (wid >> 1) + 1, 0.07216878364870322f * 1.4426950408889634f);
.LBB0_100:
	s_cmp_lt_u32 s58, 4
	s_cbranch_scc1 .Lat_prio_skip
	s_setprio 1

; #define MFMA32(a, b, c) __builtin_amdgcn_mfma_f32_32x32x16_bf16((a), (b), (c), 0, 0, 0)
; #define ATT_LDK(buf, g) do { _Pragma("unroll") for (int kk = 0; kk < 2; ++kk) { \
;                 ka[buf][kk][0] = *(const LAS bf16x8*)(Kb + r * KSTR + (2 * (g) + kk) * 32 + hh * 16); ka[buf][kk][1] = *(const LAS bf16x8*)(Kb + (32 + r) * KSTR + (2 * (g) + kk) * 32 + hh * 16); } } while (0)
; #define ATT_LDV(buf, d) do { _Pragma("unroll") for (int kb = 0; kb < 2; ++kb) _Pragma("unroll") for (int s = 0; s < 2; ++s) { \
;                 const LAS unsigned char* p_ = Vb + vlane + (32 * kb + 16 * s) * VSTR + (d) * 64; vl[buf][2 * kb + s] = trread(p_); vh[buf][2 * kb + s] = trread(p_ + 8 * VSTR); } } while (0)
; template <int NKS, bool ALLIN = false> ...
;     ...
;             f32x16 s0, s1;
; #pragma unroll
;             for (int i = 0; i < 16; ++i) { s0[i] = 0.f; s1[i] = 0.f; }
;             bf16x8 ka[2][2][2];
;     ...
;             ATT_LDK(0, 0); ATT_LDK(1, 1);
;             __builtin_amdgcn_sched_barrier(0);
; #pragma unroll
;             for (int g = 0; g < NKS / 2; ++g) {
; #pragma unroll
;                 for (int kk = 0; kk < 2; ++kk) { s0 = MFMA32(ka[g & 1][kk][0], qf[2 * g + kk], s0); s1 = MFMA32(ka[g & 1][kk][1], qf[2 * g + kk], s1); }
;                 __builtin_amdgcn_sched_barrier(0);
;                 if (g + 2 < NKS / 2) { ATT_LDK(g & 1, g + 2); __builtin_amdgcn_sched_barrier(0); }
;             }
;     ...
;             s16x4 vl[2][4], vh[2][4];
;     ...
;             ATT_LDV(0, 0); ATT_LDV(1, 1);
;             __builtin_amdgcn_sched_barrier(0);
;             float mx = -INFINITY;
; #pragma unroll
;             for (int i = 0; i < 16; ++i) mx = fmaxf(mx, fmaxf(s0[i], s1[i]));
;             mx = fmaxf(mx, __shfl_xor(mx, 32)) * c2;
.LBB0_108:
	s_and_b32 s19, s22, 1
	s_mul_i32 s22, s19, 0x6400
	v_add_u32_e32 v0, s22, v215
	ds_read_b128 v[2:5], v0
	ds_read_b128 v[6:9], v0 offset:32
	ds_read_b128 v[10:13], v0 offset:12800
	ds_read_b128 v[180:183], v0 offset:12832
	ds_read_b128 v[184:187], v0 offset:64
	ds_read_b128 v[188:191], v0 offset:96
	ds_read_b128 v[192:195], v0 offset:12864
	ds_read_b128 v[196:199], v0 offset:12896
	s_mulk_i32 s19, 0x5000
	s_waitcnt lgkmcnt(7)
	v_mfma_f32_32x32x16_bf16 v[96:111], v[2:5], v[132:135], 0
	s_waitcnt lgkmcnt(5)
	v_mfma_f32_32x32x16_bf16 v[80:95], v[10:13], v[132:135], 0
	v_mfma_f32_32x32x16_bf16 v[96:111], v[6:9], v[136:139], v[96:111]
	s_waitcnt lgkmcnt(4)
	v_mfma_f32_32x32x16_bf16 v[80:95], v[180:183], v[136:139], v[80:95]
	ds_read_b128 v[2:5], v0 offset:128
	ds_read_b128 v[6:9], v0 offset:160
	ds_read_b128 v[10:13], v0 offset:12928
	ds_read_b128 v[180:183], v0 offset:12960
	s_waitcnt lgkmcnt(7)
	v_mfma_f32_32x32x16_bf16 v[96:111], v[184:187], v[140:143], v[96:111]
	s_waitcnt lgkmcnt(5)
	v_mfma_f32_32x32x16_bf16 v[80:95], v[192:195], v[140:143], v[80:95]
	v_mfma_f32_32x32x16_bf16 v[96:111], v[188:191], v[144:147], v[96:111]
	s_waitcnt lgkmcnt(4)
	v_mfma_f32_32x32x16_bf16 v[80:95], v[196:199], v[144:147], v[80:95]
	ds_read_b128 v[184:187], v0 offset:192
	ds_read_b128 v[188:191], v0 offset:224
	ds_read_b128 v[192:195], v0 offset:12992
	ds_read_b128 v[196:199], v0 offset:13024
	s_waitcnt lgkmcnt(7)
	v_mfma_f32_32x32x16_bf16 v[96:111], v[2:5], v[148:151], v[96:111]
	s_waitcnt lgkmcnt(5)
	v_mfma_f32_32x32x16_bf16 v[80:95], v[10:13], v[148:151], v[80:95]
	v_mfma_f32_32x32x16_bf16 v[96:111], v[6:9], v[152:155], v[96:111]
	s_waitcnt lgkmcnt(4)
	v_mfma_f32_32x32x16_bf16 v[80:95], v[180:183], v[152:155], v[80:95]
	ds_read_b128 v[2:5], v0 offset:256
	ds_read_b128 v[6:9], v0 offset:288
	ds_read_b128 v[10:13], v0 offset:13056
	ds_read_b128 v[180:183], v0 offset:13088
	s_waitcnt lgkmcnt(7)
	v_mfma_f32_32x32x16_bf16 v[96:111], v[184:187], v[156:159], v[96:111]
	s_waitcnt lgkmcnt(5)
	v_mfma_f32_32x32x16_bf16 v[80:95], v[192:195], v[156:159], v[80:95]
	v_mfma_f32_32x32x16_bf16 v[96:111], v[188:191], v[160:163], v[96:111]
	s_waitcnt lgkmcnt(4)
	v_mfma_f32_32x32x16_bf16 v[80:95], v[196:199], v[160:163], v[80:95]
	ds_read_b128 v[184:187], v0 offset:320
	ds_read_b128 v[188:191], v0 offset:352
	ds_read_b128 v[192:195], v0 offset:13120
	ds_read_b128 v[196:199], v0 offset:13152
	s_waitcnt lgkmcnt(7)
	v_mfma_f32_32x32x16_bf16 v[96:111], v[2:5], v[164:167], v[96:111]
	s_waitcnt lgkmcnt(5)
	v_mfma_f32_32x32x16_bf16 v[80:95], v[10:13], v[164:167], v[80:95]
	v_mfma_f32_32x32x16_bf16 v[96:111], v[6:9], v[168:171], v[96:111]
	s_waitcnt lgkmcnt(4)
	v_mfma_f32_32x32x16_bf16 v[80:95], v[180:183], v[168:171], v[80:95]
	s_waitcnt lgkmcnt(3)
	v_mfma_f32_32x32x16_bf16 v[96:111], v[184:187], v[172:175], v[96:111]
	s_waitcnt lgkmcnt(1)
	v_mfma_f32_32x32x16_bf16 v[80:95], v[192:195], v[172:175], v[80:95]
	v_mfma_f32_32x32x16_bf16 v[96:111], v[188:191], v[176:179], v[96:111]
	s_waitcnt lgkmcnt(0)
	v_mfma_f32_32x32x16_bf16 v[80:95], v[196:199], v[176:179], v[80:95]
	v_add_u32_e32 v222, s19, v213
	v_add_u32_e32 v218, 0xc800, v222
	ds_read_b64_tr_b16 v[184:185], v222 offset:51200
	ds_read_b64_tr_b16 v[186:187], v222 offset:53760
	ds_read_b64_tr_b16 v[182:183], v222 offset:53824
	ds_read_b64_tr_b16 v[180:181], v222 offset:51264
	ds_read_b64_tr_b16 v[196:197], v222 offset:56320
	ds_read_b64_tr_b16 v[198:199], v222 offset:58880
	ds_read_b64_tr_b16 v[12:13], v222 offset:58944
	ds_read_b64_tr_b16 v[10:11], v222 offset:56384
	ds_read_b64_tr_b16 v[192:193], v222 offset:61440
	ds_read_b64_tr_b16 v[194:195], v222 offset:64000
	ds_read_b64_tr_b16 v[8:9], v222 offset:64064
	ds_read_b64_tr_b16 v[6:7], v222 offset:61504
	ds_read_b64_tr_b16 v[188:189], v218 offset:15360
	ds_read_b64_tr_b16 v[190:191], v218 offset:17920
	ds_read_b64_tr_b16 v[4:5], v218 offset:17984
	ds_read_b64_tr_b16 v[2:3], v218 offset:15424
	v_max_f32_e32 v0, v80, v80
	v_max_f32_e32 v14, v96, v96
	v_max_f32_e32 v0, v14, v0
	v_max_f32_e32 v14, v81, v81
	v_max_f32_e32 v15, v97, v97
	v_max_f32_e32 v14, v15, v14
	v_max3_f32 v0, v0, s73, v14
	v_max_f32_e32 v14, v82, v82
	v_max_f32_e32 v15, v98, v98
	v_max_f32_e32 v14, v15, v14
	v_max_f32_e32 v15, v83, v83
	v_max_f32_e32 v223, v99, v99
	v_max_f32_e32 v15, v223, v15
	v_max3_f32 v0, v0, v14, v15
	v_max_f32_e32 v14, v84, v84
	v_max_f32_e32 v15, v100, v100
	v_max_f32_e32 v14, v15, v14
	v_max_f32_e32 v15, v85, v85
	v_max_f32_e32 v223, v101, v101
	v_max_f32_e32 v15, v223, v15
	v_max3_f32 v0, v0, v14, v15
	v_max_f32_e32 v14, v86, v86
	v_max_f32_e32 v15, v102, v102
	v_max_f32_e32 v14, v15, v14
	v_max_f32_e32 v15, v87, v87
	v_max_f32_e32 v223, v103, v103
	v_max_f32_e32 v15, v223, v15
	v_max3_f32 v0, v0, v14, v15
	v_max_f32_e32 v14, v88, v88
	v_max_f32_e32 v15, v104, v104
	v_max_f32_e32 v14, v15, v14
	v_max_f32_e32 v15, v89, v89
	v_max_f32_e32 v223, v105, v105
	v_max_f32_e32 v15, v223, v15
	v_max3_f32 v0, v0, v14, v15
	v_max_f32_e32 v14, v90, v90
	v_max_f32_e32 v15, v106, v106
	v_max_f32_e32 v14, v15, v14
	v_max_f32_e32 v15, v91, v91
	v_max_f32_e32 v223, v107, v107
	v_max_f32_e32 v15, v223, v15
	v_max3_f32 v0, v0, v14, v15
	v_max_f32_e32 v14, v92, v92
	v_max_f32_e32 v15, v108, v108
	v_max_f32_e32 v14, v15, v14
	v_max_f32_e32 v15, v93, v93
	v_max_f32_e32 v223, v109, v109
	v_max_f32_e32 v15, v223, v15
	v_max3_f32 v0, v0, v14, v15
	v_max_f32_e32 v14, v94, v94
	v_max_f32_e32 v15, v110, v110
	v_max_f32_e32 v14, v15, v14
	v_max_f32_e32 v15, v95, v95
	v_max_f32_e32 v223, v111, v111
	v_max_f32_e32 v15, v223, v15
	v_max3_f32 v0, v0, v14, v15
	v_and_b32_e32 v15, 64, v220
	v_xor_b32_e32 v14, 32, v220
	v_add_u32_e32 v15, 64, v15
	v_cmp_lt_i32_e32 vcc, v14, v15
	s_nop 1
	v_cndmask_b32_e32 v14, v220, v14, vcc
	v_lshlrev_b32_e32 v14, 2, v14
	ds_bpermute_b32 v14, v14, v0
	s_waitcnt lgkmcnt(0)
; #define MFMA32(a, b, c) __builtin_amdgcn_mfma_f32_32x32x16_bf16((a), (b), (c), 0, 0, 0)
; __device__ __forceinline__ bf16x8 cat44(s16x4 lo, s16x4 hi) { return (bf16x8){lo[0], lo[1], lo[2], lo[3], hi[0], hi[1], hi[2], hi[3]}; }
; #define ATT_LDV(buf, d) do { _Pragma("unroll") for (int kb = 0; kb < 2; ++kb) _Pragma("unroll") for (int s = 0; s < 2; ++s) { \
;                 const LAS unsigned char* p_ = Vb + vlane + (32 * kb + 16 * s) * VSTR + (d) * 64; vl[buf][2 * kb + s] = trread(p_); vh[buf][2 * kb + s] = trread(p_ + 8 * VSTR); } } while (0)
; template <int NKS, bool ALLIN = false> ...
;     ...
;             float mx = -INFINITY;
; #pragma unroll
;             for (int i = 0; i < 16; ++i) mx = fmaxf(mx, fmaxf(s0[i], s1[i]));
;             mx = fmaxf(mx, __shfl_xor(mx, 32)) * c2;
;             const float mnew = fmaxf(mrun, mx), alpha = __builtin_amdgcn_exp2f(mrun - mnew); mrun = mnew;
;             float ls = 0.f;
; #pragma unroll
;             for (int i = 0; i < 16; ++i) { s0[i] = __builtin_amdgcn_exp2f(fmaf(s0[i], c2, -mnew)); s1[i] = __builtin_amdgcn_exp2f(fmaf(s1[i], c2, -mnew)); ls += s0[i] + s1[i]; }
;             lrun = lrun * alpha + ls;
; #pragma unroll
;             for (int d = 0; d < 4; ++d)
; #pragma unroll
;                 for (int i = 0; i < 16; ++i) o[d][i] *= alpha;
;             bf16x8 pf[4];
;             pf[0] = packacc8(s0, 0); pf[1] = packacc8(s0, 8); pf[2] = packacc8(s1, 0); pf[3] = packacc8(s1, 8);
;             __builtin_amdgcn_sched_barrier(0);
; #pragma unroll
;             for (int d = 0; d < 4; ++d) {
; #pragma unroll
;                 for (int j = 0; j < 4; ++j) o[d] = MFMA32(cat44(vl[d & 1][j], vh[d & 1][j]), pf[j], o[d]);
;                 __builtin_amdgcn_sched_barrier(0);
;                 if (d + 2 < 4) { ATT_LDV(d & 1, d + 2); __builtin_amdgcn_sched_barrier(0); }
	v_max_f32_e32 v14, v14, v14
	v_max_f32_e32 v0, v0, v14
	v_mul_f32_e32 v0, 0x3dd53b94, v0
	v_max_f32_e32 v14, v219, v219
	v_max_f32_e32 v223, v14, v0
	v_fma_f32 v14, v98, s80, -v223
	v_exp_f32_e32 v234, v14
	v_fma_f32 v14, v82, s80, -v223
	v_fma_f32 v0, v96, s80, -v223
	v_exp_f32_e32 v235, v14
	v_fma_f32 v14, v99, s80, -v223
	v_exp_f32_e32 v224, v0
	v_fma_f32 v0, v80, s80, -v223
	v_exp_f32_e32 v236, v14
	v_fma_f32 v14, v83, s80, -v223
	v_exp_f32_e32 v225, v0
	v_fma_f32 v0, v97, s80, -v223
	v_exp_f32_e32 v237, v14
	v_fma_f32 v14, v100, s80, -v223
	v_exp_f32_e32 v226, v0
	v_fma_f32 v0, v81, s80, -v223
	v_exp_f32_e32 v81, v14
	v_fma_f32 v14, v84, s80, -v223
	v_exp_f32_e32 v15, v14
	v_fma_f32 v14, v101, s80, -v223
	v_fma_f32 v82, v102, s80, -v223
	v_exp_f32_e32 v80, v14
	v_fma_f32 v14, v85, s80, -v223
	v_exp_f32_e32 v85, v82
	v_fma_f32 v82, v86, s80, -v223
	v_fma_f32 v86, v104, s80, -v223
	v_exp_f32_e32 v101, v86
	v_fma_f32 v86, v88, s80, -v223
	v_fma_f32 v88, v106, s80, -v223
	v_exp_f32_e32 v83, v82
	v_fma_f32 v82, v103, s80, -v223
	v_exp_f32_e32 v103, v88
	v_fma_f32 v88, v90, s80, -v223
	v_exp_f32_e32 v84, v82
	v_fma_f32 v82, v87, s80, -v223
	v_exp_f32_e32 v87, v86
	v_fma_f32 v86, v105, s80, -v223
	v_exp_f32_e32 v105, v88
	v_fma_f32 v88, v107, s80, -v223
	v_exp_f32_e32 v102, v88
	v_fma_f32 v88, v91, s80, -v223
	v_exp_f32_e32 v227, v0
	v_exp_f32_e32 v104, v88
	v_fma_f32 v88, v108, s80, -v223
	v_exp_f32_e32 v107, v88
	v_fma_f32 v88, v92, s80, -v223
	v_exp_f32_e32 v231, v88
	v_fma_f32 v88, v109, s80, -v223
	v_sub_f32_e32 v0, v219, v223
	v_add_f32_e32 v219, v224, v225
	v_exp_f32_e32 v14, v14
	v_exp_f32_e32 v106, v88
	v_fma_f32 v88, v93, s80, -v223
	v_add_f32_e32 v229, v226, v227
	v_exp_f32_e32 v230, v88
	v_fma_f32 v88, v110, s80, -v223
	v_add_f32_e32 v110, 0, v219
	v_exp_f32_e32 v82, v82
	v_add_f32_e32 v238, v234, v235
	v_add_f32_e32 v110, v229, v110
	v_add_f32_e32 v239, v236, v237
	v_exp_f32_e32 v100, v86
	v_fma_f32 v86, v89, s80, -v223
	v_add_f32_e32 v110, v238, v110
	v_pk_add_f32 v[96:97], v[80:81], v[14:15]
	v_exp_f32_e32 v86, v86
	v_add_f32_e32 v110, v239, v110
	v_exp_f32_e32 v109, v88
	v_fma_f32 v88, v94, s80, -v223
	v_add_f32_e32 v97, v97, v110
	v_pk_add_f32 v[98:99], v[84:85], v[82:83]
	v_exp_f32_e32 v233, v88
	v_fma_f32 v88, v111, s80, -v223
	v_add_f32_e32 v96, v96, v97
	v_exp_f32_e32 v108, v88
	v_fma_f32 v88, v95, s80, -v223
	v_add_f32_e32 v96, v99, v96
	v_exp_f32_e32 v232, v88
	v_pk_add_f32 v[88:89], v[100:101], v[86:87]
	v_add_f32_e32 v96, v98, v96
	v_add_f32_e32 v89, v89, v96
	v_pk_add_f32 v[90:91], v[102:103], v[104:105]
	v_add_f32_e32 v88, v88, v89
	v_add_f32_e32 v88, v91, v88
	v_exp_f32_e32 v0, v0
	v_pk_add_f32 v[92:93], v[106:107], v[230:231]
	v_add_f32_e32 v88, v90, v88
	v_add_f32_e32 v88, v93, v88
	v_pk_add_f32 v[94:95], v[108:109], v[232:233]
	v_add_f32_e32 v88, v92, v88
	v_add_f32_e32 v88, v95, v88
	v_pk_mul_f32 v[78:79], v[78:79], v[0:1] op_sel_hi:[1,0]
	v_pk_mul_f32 v[76:77], v[76:77], v[0:1] op_sel_hi:[1,0]
	v_pk_mul_f32 v[74:75], v[74:75], v[0:1] op_sel_hi:[1,0]
	v_pk_mul_f32 v[72:73], v[72:73], v[0:1] op_sel_hi:[1,0]
	v_pk_mul_f32 v[70:71], v[70:71], v[0:1] op_sel_hi:[1,0]
	v_pk_mul_f32 v[68:69], v[68:69], v[0:1] op_sel_hi:[1,0]
	v_pk_mul_f32 v[66:67], v[66:67], v[0:1] op_sel_hi:[1,0]
	v_pk_mul_f32 v[64:65], v[64:65], v[0:1] op_sel_hi:[1,0]
	v_pk_mul_f32 v[62:63], v[62:63], v[0:1] op_sel_hi:[1,0]
	v_pk_mul_f32 v[60:61], v[60:61], v[0:1] op_sel_hi:[1,0]
	v_pk_mul_f32 v[58:59], v[58:59], v[0:1] op_sel_hi:[1,0]
	v_pk_mul_f32 v[56:57], v[56:57], v[0:1] op_sel_hi:[1,0]
	v_pk_mul_f32 v[54:55], v[54:55], v[0:1] op_sel_hi:[1,0]
	v_pk_mul_f32 v[52:53], v[52:53], v[0:1] op_sel_hi:[1,0]
	v_pk_mul_f32 v[50:51], v[50:51], v[0:1] op_sel_hi:[1,0]
	v_pk_mul_f32 v[48:49], v[48:49], v[0:1] op_sel_hi:[1,0]
	v_pk_mul_f32 v[46:47], v[46:47], v[0:1] op_sel_hi:[1,0]
	v_pk_mul_f32 v[44:45], v[44:45], v[0:1] op_sel_hi:[1,0]
	v_pk_mul_f32 v[42:43], v[42:43], v[0:1] op_sel_hi:[1,0]
	v_pk_mul_f32 v[40:41], v[40:41], v[0:1] op_sel_hi:[1,0]
	v_pk_mul_f32 v[38:39], v[38:39], v[0:1] op_sel_hi:[1,0]
	v_pk_mul_f32 v[36:37], v[36:37], v[0:1] op_sel_hi:[1,0]
	v_pk_mul_f32 v[34:35], v[34:35], v[0:1] op_sel_hi:[1,0]
	v_pk_mul_f32 v[32:33], v[32:33], v[0:1] op_sel_hi:[1,0]
	v_pk_mul_f32 v[30:31], v[30:31], v[0:1] op_sel_hi:[1,0]
	v_pk_mul_f32 v[28:29], v[28:29], v[0:1] op_sel_hi:[1,0]
	v_pk_mul_f32 v[26:27], v[26:27], v[0:1] op_sel_hi:[1,0]
	v_pk_mul_f32 v[24:25], v[24:25], v[0:1] op_sel_hi:[1,0]
	v_pk_mul_f32 v[22:23], v[22:23], v[0:1] op_sel_hi:[1,0]
	v_pk_mul_f32 v[20:21], v[20:21], v[0:1] op_sel_hi:[1,0]
	v_pk_mul_f32 v[18:19], v[18:19], v[0:1] op_sel_hi:[1,0]
	v_pk_mul_f32 v[16:17], v[16:17], v[0:1] op_sel_hi:[1,0]
	v_add_f32_e32 v219, v94, v88
	v_cvt_pk_bf16_f32 v88, v224, v226
	v_cvt_pk_bf16_f32 v89, v234, v236
	v_cvt_pk_bf16_f32 v90, v81, v80
	v_cvt_pk_bf16_f32 v91, v85, v84
	v_cvt_pk_bf16_f32 v92, v101, v100
	v_cvt_pk_bf16_f32 v93, v103, v102
	v_cvt_pk_bf16_f32 v94, v107, v106
	v_cvt_pk_bf16_f32 v95, v109, v108
	v_cvt_pk_bf16_f32 v96, v225, v227
	v_cvt_pk_bf16_f32 v97, v235, v237
	v_cvt_pk_bf16_f32 v98, v15, v14
	v_cvt_pk_bf16_f32 v99, v83, v82
	v_cvt_pk_bf16_f32 v80, v87, v86
	v_cvt_pk_bf16_f32 v81, v105, v104
	v_cvt_pk_bf16_f32 v82, v231, v230
	v_cvt_pk_bf16_f32 v83, v233, v232
	s_nop 0
	v_mfma_f32_32x32x16_bf16 v[64:79], v[184:187], v[88:91], v[64:79]
	v_mfma_f32_32x32x16_bf16 v[64:79], v[196:199], v[92:95], v[64:79]
	v_mfma_f32_32x32x16_bf16 v[64:79], v[192:195], v[96:99], v[64:79]
	v_mfma_f32_32x32x16_bf16 v[64:79], v[188:191], v[80:83], v[64:79]
	ds_read_b64_tr_b16 v[84:85], v222 offset:51328
	ds_read_b64_tr_b16 v[86:87], v222 offset:53888
	ds_read_b64_tr_b16 v[100:101], v222 offset:56448
	ds_read_b64_tr_b16 v[102:103], v222 offset:59008
	ds_read_b64_tr_b16 v[104:105], v222 offset:61568
	ds_read_b64_tr_b16 v[106:107], v222 offset:64128
	ds_read_b64_tr_b16 v[108:109], v218 offset:15488
	ds_read_b64_tr_b16 v[110:111], v218 offset:18048
	v_mfma_f32_32x32x16_bf16 v[48:63], v[180:183], v[88:91], v[48:63]
	v_mfma_f32_32x32x16_bf16 v[48:63], v[10:13], v[92:95], v[48:63]
	v_mfma_f32_32x32x16_bf16 v[48:63], v[6:9], v[96:99], v[48:63]
	v_mfma_f32_32x32x16_bf16 v[48:63], v[2:5], v[80:83], v[48:63]
	ds_read_b64_tr_b16 v[2:3], v222 offset:51392
	ds_read_b64_tr_b16 v[4:5], v222 offset:53952
	ds_read_b64_tr_b16 v[6:7], v222 offset:56512
	ds_read_b64_tr_b16 v[8:9], v222 offset:59072
	ds_read_b64_tr_b16 v[10:11], v222 offset:61632
	ds_read_b64_tr_b16 v[12:13], v222 offset:64192
	ds_read_b64_tr_b16 v[180:181], v218 offset:15552
	ds_read_b64_tr_b16 v[182:183], v218 offset:18112
	s_waitcnt lgkmcnt(14)
; #define MFMA32(a, b, c) __builtin_amdgcn_mfma_f32_32x32x16_bf16((a), (b), (c), 0, 0, 0)
; __device__ __forceinline__ bf16x8 cat44(s16x4 lo, s16x4 hi) { return (bf16x8){lo[0], lo[1], lo[2], lo[3], hi[0], hi[1], hi[2], hi[3]}; }
; #define ATT_LDV(buf, d) do { _Pragma("unroll") for (int kb = 0; kb < 2; ++kb) _Pragma("unroll") for (int s = 0; s < 2; ++s) { \
;                 const LAS unsigned char* p_ = Vb + vlane + (32 * kb + 16 * s) * VSTR + (d) * 64; vl[buf][2 * kb + s] = trread(p_); vh[buf][2 * kb + s] = trread(p_ + 8 * VSTR); } } while (0)
; template <int NKS, bool ALLIN = false> ...
;     ...
;             lrun = lrun * alpha + ls;
; #pragma unroll
;             for (int d = 0; d < 4; ++d)
; #pragma unroll
;                 for (int i = 0; i < 16; ++i) o[d][i] *= alpha;
;             bf16x8 pf[4];
;             pf[0] = packacc8(s0, 0); pf[1] = packacc8(s0, 8); pf[2] = packacc8(s1, 0); pf[3] = packacc8(s1, 8);
;             __builtin_amdgcn_sched_barrier(0);
; #pragma unroll
;             for (int d = 0; d < 4; ++d) {
; #pragma unroll
;                 for (int j = 0; j < 4; ++j) o[d] = MFMA32(cat44(vl[d & 1][j], vh[d & 1][j]), pf[j], o[d]);
;                 __builtin_amdgcn_sched_barrier(0);
;                 if (d + 2 < 4) { ATT_LDV(d & 1, d + 2); __builtin_amdgcn_sched_barrier(0); }
;             }
	v_mfma_f32_32x32x16_bf16 v[32:47], v[84:87], v[88:91], v[32:47]
	s_waitcnt lgkmcnt(12)
	v_mfma_f32_32x32x16_bf16 v[32:47], v[100:103], v[92:95], v[32:47]
	s_waitcnt lgkmcnt(10)
	v_mfma_f32_32x32x16_bf16 v[32:47], v[104:107], v[96:99], v[32:47]
	s_waitcnt lgkmcnt(8)
	v_mfma_f32_32x32x16_bf16 v[32:47], v[108:111], v[80:83], v[32:47]
	s_waitcnt lgkmcnt(6)
	v_mfma_f32_32x32x16_bf16 v[16:31], v[2:5], v[88:91], v[16:31]
	s_waitcnt lgkmcnt(4)
	v_mfma_f32_32x32x16_bf16 v[16:31], v[6:9], v[92:95], v[16:31]
	s_waitcnt lgkmcnt(2)
	v_mfma_f32_32x32x16_bf16 v[16:31], v[10:13], v[96:99], v[16:31]
	s_waitcnt lgkmcnt(0)
	v_mfma_f32_32x32x16_bf16 v[16:31], v[180:183], v[80:83], v[16:31]
	v_fmac_f32_e32 v219, v214, v0
	v_mov_b32_e32 v214, v219
	v_mov_b32_e32 v219, v223
	s_andn2_b64 vcc, exec, s[16:17]
	s_cbranch_vccz .LBB0_104
	s_branch .LBB0_105
	s_nop 0
	s_nop 0
.LBB0_109:
	s_setprio 0
	s_mov_b32 s8, s34
	s_branch .LBB0_111
	s_nop 0
	s_nop 0
	s_nop 0
	s_nop 0
	s_nop 0
	s_nop 0
	s_nop 0
	s_nop 0
	s_nop 0
	s_nop 0
	s_nop 0
	s_nop 0
	s_nop 0
	s_nop 0
	s_nop 0
	s_nop 0
	s_nop 0
	s_nop 0
	s_nop 0
	s_nop 0
	s_nop 0
	s_nop 0
	s_nop 0
	s_nop 0
	s_nop 0
	s_nop 0
	s_nop 0
	s_nop 0
	s_nop 0
	s_nop 0
	s_nop 0
	s_nop 0
	s_nop 0
	s_nop 0
	s_nop 0
	s_nop 0
	s_nop 0
	s_nop 0
	s_nop 0
	s_nop 0
	s_nop 0
	s_nop 0
	s_nop 0
	s_nop 0
	s_nop 0
	s_nop 0
	s_nop 0
	s_nop 0
	s_nop 0
	s_nop 0
	s_nop 0
	s_nop 0
	s_nop 0
	s_nop 0
	s_nop 0
	s_nop 0
	s_nop 0
	s_nop 0
	s_nop 0
	s_nop 0
	s_nop 0
	s_nop 0
	s_nop 0
	s_nop 0
	s_nop 0
	s_nop 0
	s_nop 0
	s_nop 0
	s_nop 0
	s_nop 0
	s_nop 0
	s_nop 0
	s_nop 0
	s_nop 0
	s_nop 0
	s_nop 0
	s_nop 0
	s_nop 0
	s_nop 0
	s_nop 0
	s_nop 0
	s_nop 0
	s_nop 0
	s_nop 0
	s_nop 0
	s_nop 0
	s_nop 0
	s_nop 0
	s_nop 0
	s_nop 0
	s_nop 0
	s_nop 0
	s_nop 0
	s_nop 0
	s_nop 0
	s_nop 0
	s_nop 0
	s_nop 0
	s_nop 0
	s_nop 0
	s_nop 0
	s_nop 0
	s_nop 0
	s_nop 0
	s_nop 0
	s_nop 0
	s_nop 0
	s_nop 0
	s_nop 0
	s_nop 0
	s_nop 0
	s_nop 0
	s_nop 0
	s_nop 0
	s_nop 0
	s_nop 0
	s_nop 0
	s_nop 0
	s_nop 0
	s_nop 0
	s_nop 0
	s_nop 0
	s_nop 0
	s_nop 0
	s_nop 0
	s_nop 0
	s_nop 0
	s_nop 0
	s_nop 0
	s_nop 0
	s_nop 0
	s_nop 0
	s_nop 0
	s_nop 0
	s_nop 0
	s_nop 0
	s_nop 0
	s_nop 0
	s_nop 0
	s_nop 0
	s_nop 0
	s_nop 0
	s_nop 0
	s_nop 0
	s_nop 0
	s_nop 0
	s_nop 0
	s_nop 0
	s_nop 0
	s_nop 0
	s_nop 0
	s_nop 0
	s_nop 0
	s_nop 0
	s_nop 0
	s_nop 0
	s_nop 0
	s_nop 0
	s_nop 0
	s_nop 0
	s_nop 0
	s_nop 0
	s_nop 0
	s_nop 0
	s_nop 0
	s_nop 0
	s_nop 0
	s_nop 0
	s_nop 0
	s_nop 0
	s_nop 0
	s_nop 0
	s_nop 0
	s_nop 0
	s_nop 0
	s_nop 0
	s_nop 0
	s_nop 0
	s_nop 0
	s_nop 0
	s_nop 0
	s_nop 0
	s_nop 0
	s_nop 0
	s_nop 0
	s_nop 0
	s_nop 0
	s_nop 0
	s_nop 0
	s_nop 0
	s_nop 0
	s_nop 0
	s_nop 0
	s_nop 0
	s_nop 0
	s_nop 0
	s_nop 0
	s_nop 0
	s_nop 0
	s_nop 0
	s_nop 0
	s_nop 0
	s_nop 0
	s_nop 0
	s_nop 0
	s_nop 0
	s_nop 0
	s_nop 0
	s_nop 0
	s_nop 0
	s_nop 0
	s_nop 0
	s_nop 0
	s_nop 0
	s_nop 0
	s_nop 0
	s_nop 0
	s_nop 0
	s_nop 0
	s_nop 0
	s_nop 0
	s_nop 0
	s_nop 0
	s_nop 0
	s_nop 0
	s_nop 0
	s_nop 0
	s_nop 0
	s_nop 0
	s_nop 0
	s_nop 0
	s_nop 0
	s_nop 0
	s_nop 0
	s_nop 0
	s_nop 0
	s_nop 0
	s_nop 0
	s_nop 0
	s_nop 0
	s_nop 0
	s_nop 0
	s_nop 0
	s_nop 0
	s_nop 0
	s_nop 0
	s_nop 0
	s_nop 0
	s_nop 0
	s_nop 0
	s_nop 0
	s_nop 0
	s_nop 0
	s_nop 0
	s_nop 0
	s_nop 0
	s_nop 0
	s_nop 0
	s_nop 0
	s_nop 0
	s_nop 0
	s_nop 0
	s_nop 0
	s_nop 0
	s_nop 0
	s_nop 0
	s_nop 0
	s_nop 0
	s_nop 0
	s_nop 0
	s_nop 0
	s_nop 0
	s_nop 0
	s_nop 0
	s_nop 0
	s_nop 0
	s_nop 0
	s_nop 0
	s_nop 0
	s_nop 0
	s_nop 0
	s_nop 0
	s_nop 0
	s_nop 0
	s_nop 0
	s_nop 0
	s_nop 0
	s_nop 0
	s_nop 0
	s_nop 0
	s_nop 0
	s_nop 0
	s_nop 0
	s_nop 0
	s_nop 0
	s_nop 0
	s_nop 0
	s_nop 0
	s_nop 0
	s_nop 0
	s_nop 0
	s_nop 0
	s_nop 0
	s_nop 0
	s_nop 0
	s_nop 0
	s_nop 0
	s_nop 0
	s_nop 0
	s_nop 0
	s_nop 0
	s_nop 0
	s_nop 0
	s_nop 0
	s_nop 0
	s_nop 0
	s_nop 0
	s_nop 0
	s_nop 0
	s_nop 0
	s_nop 0
	s_nop 0
	s_nop 0
	s_nop 0
	s_nop 0
	s_nop 0
	s_nop 0
	s_nop 0
	s_nop 0
	s_nop 0
	s_nop 0
	s_nop 0
	s_nop 0
	s_nop 0
	s_nop 0
	s_nop 0
	s_nop 0
	s_nop 0
	s_nop 0
	s_nop 0
	s_nop 0
	s_nop 0
	s_nop 0
	s_nop 0
	s_nop 0
	s_nop 0
	s_nop 0
	s_nop 0
	s_nop 0
	s_nop 0
	s_nop 0
	s_nop 0
	s_nop 0
	s_nop 0
	s_nop 0
	s_nop 0
	s_nop 0
	s_nop 0
	s_nop 0
	s_nop 0
	s_nop 0
	s_nop 0
	s_nop 0
	s_nop 0
	s_nop 0
	s_nop 0
	s_nop 0
	s_nop 0
